# attention QK: 4 K-fragment LDS reads in flight (counted lgkmcnt) instead of read-wait-MFMA serialization
# speedup vs baseline: 1.0770x; 1.0110x over previous
.LBB0_638:
	s_cmp_le_i32 s47, s79
	s_cselect_b64 s[18:19], -1, 0
	s_and_b64 s[18:19], s[26:27], s[18:19]
	s_andn2_b64 vcc, exec, s[18:19]
	s_cbranch_vccnz .LBB0_648
	s_setprio 1
	s_mul_i32 s2, s66, 0x2400
	v_add_u32_e32 v1, s2, v195
	ds_read_b128 v[2:5], v1
	ds_read_b128 v[6:9], v1 offset:4608
	ds_read_b128 v[10:13], v1 offset:32
	ds_read_b128 v[168:171], v1 offset:4640
	s_cmp_ge_i32 s47, s84
	s_cselect_b64 s[18:19], -1, 0
	s_cmp_lt_i32 s47, s84
	s_cselect_b64 vcc, -1, 0
	v_cndmask_b32_e32 v80, 0, v251, vcc
	v_mov_b32_e32 v81, v80
	v_mov_b32_e32 v82, v80
	v_mov_b32_e32 v83, v80
	v_mov_b32_e32 v84, v80
	v_mov_b32_e32 v85, v80
	v_mov_b32_e32 v86, v80
	v_mov_b32_e32 v87, v80
	v_mov_b32_e32 v88, v80
	v_mov_b32_e32 v89, v80
	v_mov_b32_e32 v90, v80
	v_mov_b32_e32 v91, v80
	v_mov_b32_e32 v92, v80
	v_mov_b32_e32 v93, v80
	v_mov_b32_e32 v94, v80
	v_mov_b32_e32 v95, v80
	s_waitcnt lgkmcnt(3)
	s_nop 0
	v_mfma_f32_32x32x16_bf16 v[96:111], v[2:5], v[132:135], v[80:95]
	ds_read_b128 v[2:5], v1 offset:64
	s_waitcnt lgkmcnt(3)
	v_mfma_f32_32x32x16_bf16 v[80:95], v[6:9], v[132:135], v[80:95]
	ds_read_b128 v[6:9], v1 offset:4672
	s_waitcnt lgkmcnt(3)
	v_mfma_f32_32x32x16_bf16 v[96:111], v[10:13], v[128:131], v[96:111]
	ds_read_b128 v[10:13], v1 offset:96
	s_waitcnt lgkmcnt(3)
	v_mfma_f32_32x32x16_bf16 v[80:95], v[168:171], v[128:131], v[80:95]
	ds_read_b128 v[168:171], v1 offset:4704
	s_waitcnt lgkmcnt(3)
	v_mfma_f32_32x32x16_bf16 v[96:111], v[2:5], v[140:143], v[96:111]
	s_waitcnt lgkmcnt(2)
	v_mfma_f32_32x32x16_bf16 v[80:95], v[6:9], v[140:143], v[80:95]
	s_waitcnt lgkmcnt(1)
	v_mfma_f32_32x32x16_bf16 v[96:111], v[10:13], v[136:139], v[96:111]
	s_waitcnt lgkmcnt(0)
	v_mfma_f32_32x32x16_bf16 v[80:95], v[168:171], v[136:139], v[80:95]
	s_setprio 0
	s_mul_i32 s2, s66, 0x4400
	v_add_u32_e32 v1, s2, v248
	v_add_u32_e32 v2, 0x6800, v1
	ds_read2_b64 v[6:9], v2 offset0:128 offset1:130
	ds_read2_b64 v[10:13], v2 offset0:132 offset1:134
	ds_read2_b64 v[168:171], v2 offset0:136 offset1:138
	ds_read2_b64 v[2:5], v2 offset0:140 offset1:142
	s_mov_b64 s[22:23], -1
	s_and_b64 vcc, exec, s[18:19]
	v_add_u32_e32 v14, v252, v227
	s_cbranch_vccz .LBB0_641
	v_max_i32_e32 v15, 0xffffff01, v14
	v_lshl_add_u32 v15, v15, 2, s16
	v_max_i32_e32 v112, 0xffffff00, v14
	v_max_i32_e32 v113, 0xfffffeff, v14
	v_max_i32_e32 v114, 0xfffffefe, v14
	v_max_i32_e32 v115, 0xfffffef9, v14
	v_max_i32_e32 v116, 0xfffffef8, v14
	v_max_i32_e32 v117, 0xfffffef7, v14
	v_max_i32_e32 v118, 0xfffffef6, v14
	v_lshl_add_u32 v112, v112, 2, s16
	v_lshl_add_u32 v113, v113, 2, s16
	v_lshl_add_u32 v114, v114, 2, s16
	v_lshl_add_u32 v115, v115, 2, s16
	v_lshl_add_u32 v116, v116, 2, s16
	v_lshl_add_u32 v117, v117, 2, s16
	v_lshl_add_u32 v118, v118, 2, s16
	ds_read_b32 v15, v15 offset:1020
	ds_read_b32 v119, v112 offset:1024
	ds_read_b32 v120, v113 offset:1028
	ds_read_b32 v121, v114 offset:1032
	ds_read_b32 v122, v115 offset:1052
	ds_read_b32 v123, v116 offset:1056
	ds_read_b32 v124, v117 offset:1060
	ds_read_b32 v125, v118 offset:1064
	s_waitcnt lgkmcnt(7)
	v_add_f32_e32 v15, v96, v15
	v_exp_f32_e32 v112, v15
	s_waitcnt lgkmcnt(6)
	v_add_f32_e32 v15, v97, v119
	v_exp_f32_e32 v113, v15
	s_waitcnt lgkmcnt(5)
	v_add_f32_e32 v15, v98, v120
	v_exp_f32_e32 v114, v15
	s_waitcnt lgkmcnt(4)
	v_add_f32_e32 v15, v99, v121
	v_exp_f32_e32 v115, v15
	s_waitcnt lgkmcnt(3)
	v_add_f32_e32 v116, v100, v122
	v_add_f32_e32 v15, v228, v112
	v_exp_f32_e32 v116, v116
	s_waitcnt lgkmcnt(2)
	v_add_f32_e32 v117, v101, v123
	s_waitcnt lgkmcnt(1)
	v_add_f32_e32 v118, v102, v124
	s_waitcnt lgkmcnt(0)
	v_add_f32_e32 v119, v103, v125
	v_max_i32_e32 v120, 0xfffffef1, v14
	v_max_i32_e32 v121, 0xfffffef0, v14
	v_max_i32_e32 v122, 0xfffffeef, v14
	v_max_i32_e32 v123, 0xfffffeee, v14
	v_max_i32_e32 v124, 0xfffffee9, v14
	v_max_i32_e32 v125, 0xfffffee8, v14
	v_max_i32_e32 v126, 0xfffffee7, v14
	v_max_i32_e32 v127, 0xfffffee6, v14
	v_add_f32_e32 v15, v15, v113
	v_exp_f32_e32 v117, v117
	v_lshl_add_u32 v120, v120, 2, s16
	v_lshl_add_u32 v121, v121, 2, s16
	v_lshl_add_u32 v122, v122, 2, s16
	v_lshl_add_u32 v123, v123, 2, s16
	v_lshl_add_u32 v124, v124, 2, s16
	v_lshl_add_u32 v125, v125, 2, s16
	v_lshl_add_u32 v126, v126, 2, s16
	v_lshl_add_u32 v127, v127, 2, s16
	v_add_f32_e32 v15, v15, v114
	v_exp_f32_e32 v118, v118
	ds_read_b32 v120, v120 offset:1084
	ds_read_b32 v121, v121 offset:1088
	ds_read_b32 v122, v122 offset:1092
	ds_read_b32 v123, v123 offset:1096
	ds_read_b32 v124, v124 offset:1116
	ds_read_b32 v125, v125 offset:1120
	ds_read_b32 v126, v126 offset:1124
	ds_read_b32 v127, v127 offset:1128
	v_add_f32_e32 v15, v15, v115
	v_exp_f32_e32 v119, v119
	s_waitcnt lgkmcnt(7)
	v_add_f32_e32 v120, v104, v120
	v_add_f32_e32 v15, v15, v116
	v_exp_f32_e32 v120, v120
	s_waitcnt lgkmcnt(6)
	v_add_f32_e32 v121, v105, v121
	v_add_f32_e32 v15, v15, v117
	v_exp_f32_e32 v121, v121
	s_waitcnt lgkmcnt(5)
	v_add_f32_e32 v122, v106, v122
	v_add_f32_e32 v15, v15, v118
	v_exp_f32_e32 v122, v122
	s_waitcnt lgkmcnt(4)
	v_add_f32_e32 v123, v107, v123
	v_add_f32_e32 v15, v15, v119
	v_exp_f32_e32 v123, v123
	s_waitcnt lgkmcnt(3)
	v_add_f32_e32 v124, v108, v124
	v_add_f32_e32 v15, v15, v120
	v_exp_f32_e32 v124, v124
	s_waitcnt lgkmcnt(2)
	v_add_f32_e32 v125, v109, v125
	v_add_f32_e32 v15, v15, v121
	v_exp_f32_e32 v125, v125
	s_waitcnt lgkmcnt(1)
	v_add_f32_e32 v126, v110, v126
	v_add_f32_e32 v15, v15, v122
	v_exp_f32_e32 v126, v126
	s_waitcnt lgkmcnt(0)
	v_add_f32_e32 v127, v111, v127
	v_add_f32_e32 v15, v15, v123
	v_exp_f32_e32 v127, v127
	v_add_f32_e32 v15, v15, v124
	v_add_f32_e32 v15, v15, v125
	v_add_f32_e32 v15, v15, v126
	v_add_f32_e32 v15, v15, v127
	s_mov_b64 s[22:23], 0

.LBB0_653:
	s_cmp_lt_i32 s47, s79
	s_cselect_b64 s[18:19], -1, 0
	s_and_b64 s[18:19], s[26:27], s[18:19]
	s_andn2_b64 vcc, exec, s[18:19]
	s_cbranch_vccnz .LBB0_663
	s_setprio 1
	s_mul_i32 s15, s85, 0x2400
	v_add_u32_e32 v1, s15, v195
	ds_read_b128 v[2:5], v1
	ds_read_b128 v[6:9], v1 offset:4608
	ds_read_b128 v[10:13], v1 offset:32
	ds_read_b128 v[168:171], v1 offset:4640
	s_cmp_ge_i32 s2, s84
	s_cselect_b64 s[18:19], -1, 0
	s_cmp_lt_i32 s2, s84
	s_cselect_b64 vcc, -1, 0
	v_cndmask_b32_e32 v80, 0, v251, vcc
	v_mov_b32_e32 v81, v80
	v_mov_b32_e32 v82, v80
	v_mov_b32_e32 v83, v80
	v_mov_b32_e32 v84, v80
	v_mov_b32_e32 v85, v80
	v_mov_b32_e32 v86, v80
	v_mov_b32_e32 v87, v80
	v_mov_b32_e32 v88, v80
	v_mov_b32_e32 v89, v80
	v_mov_b32_e32 v90, v80
	v_mov_b32_e32 v91, v80
	v_mov_b32_e32 v92, v80
	v_mov_b32_e32 v93, v80
	v_mov_b32_e32 v94, v80
	v_mov_b32_e32 v95, v80
	s_waitcnt lgkmcnt(3)
	s_nop 0
	v_mfma_f32_32x32x16_bf16 v[96:111], v[2:5], v[132:135], v[80:95]
	ds_read_b128 v[2:5], v1 offset:64
	s_waitcnt lgkmcnt(3)
	v_mfma_f32_32x32x16_bf16 v[80:95], v[6:9], v[132:135], v[80:95]
	ds_read_b128 v[6:9], v1 offset:4672
	s_waitcnt lgkmcnt(3)
	v_mfma_f32_32x32x16_bf16 v[96:111], v[10:13], v[128:131], v[96:111]
	ds_read_b128 v[10:13], v1 offset:96
	s_waitcnt lgkmcnt(3)
	v_mfma_f32_32x32x16_bf16 v[80:95], v[168:171], v[128:131], v[80:95]
	ds_read_b128 v[168:171], v1 offset:4704
	s_waitcnt lgkmcnt(3)
	v_mfma_f32_32x32x16_bf16 v[96:111], v[2:5], v[140:143], v[96:111]
	s_waitcnt lgkmcnt(2)
	v_mfma_f32_32x32x16_bf16 v[80:95], v[6:9], v[140:143], v[80:95]
	s_waitcnt lgkmcnt(1)
	v_mfma_f32_32x32x16_bf16 v[96:111], v[10:13], v[136:139], v[96:111]
	s_waitcnt lgkmcnt(0)
	v_mfma_f32_32x32x16_bf16 v[80:95], v[168:171], v[136:139], v[80:95]
	s_setprio 0
	s_mul_i32 s2, s85, 0x4400
	v_add_u32_e32 v1, s2, v248
	v_add_u32_e32 v2, 0x6800, v1
	ds_read2_b64 v[6:9], v2 offset0:128 offset1:130
	ds_read2_b64 v[10:13], v2 offset0:132 offset1:134
	ds_read2_b64 v[168:171], v2 offset0:136 offset1:138
	ds_read2_b64 v[2:5], v2 offset0:140 offset1:142
	s_mov_b64 s[22:23], -1
	s_and_b64 vcc, exec, s[18:19]
	s_cbranch_vccz .LBB0_656
	v_add3_u32 v14, v252, v227, 64
	v_max_i32_e32 v15, 0xffffff01, v14
	v_lshl_add_u32 v15, v15, 2, s16
	v_max_i32_e32 v112, 0xffffff00, v14
	v_max_i32_e32 v113, 0xfffffeff, v14
	v_max_i32_e32 v114, 0xfffffefe, v14
	v_max_i32_e32 v115, 0xfffffef9, v14
	v_max_i32_e32 v116, 0xfffffef8, v14
	v_max_i32_e32 v117, 0xfffffef7, v14
	v_max_i32_e32 v118, 0xfffffef6, v14
	v_lshl_add_u32 v112, v112, 2, s16
	v_lshl_add_u32 v113, v113, 2, s16
	v_lshl_add_u32 v114, v114, 2, s16
	v_lshl_add_u32 v115, v115, 2, s16
	v_lshl_add_u32 v116, v116, 2, s16
	v_lshl_add_u32 v117, v117, 2, s16
	v_lshl_add_u32 v118, v118, 2, s16
	ds_read_b32 v15, v15 offset:1020
	ds_read_b32 v119, v112 offset:1024
	ds_read_b32 v120, v113 offset:1028
	ds_read_b32 v121, v114 offset:1032
	ds_read_b32 v122, v115 offset:1052
	ds_read_b32 v123, v116 offset:1056
	ds_read_b32 v124, v117 offset:1060
	ds_read_b32 v125, v118 offset:1064
	s_waitcnt lgkmcnt(7)
	v_add_f32_e32 v15, v96, v15
	v_exp_f32_e32 v112, v15
	s_waitcnt lgkmcnt(6)
	v_add_f32_e32 v15, v97, v119
	v_exp_f32_e32 v113, v15
	s_waitcnt lgkmcnt(5)
	v_add_f32_e32 v15, v98, v120
	v_exp_f32_e32 v114, v15
	s_waitcnt lgkmcnt(4)
	v_add_f32_e32 v15, v99, v121
	v_exp_f32_e32 v115, v15
	s_waitcnt lgkmcnt(3)
	v_add_f32_e32 v116, v100, v122
	v_add_f32_e32 v15, v228, v112
	v_exp_f32_e32 v116, v116
	s_waitcnt lgkmcnt(2)
	v_add_f32_e32 v117, v101, v123
	s_waitcnt lgkmcnt(1)
	v_add_f32_e32 v118, v102, v124
	s_waitcnt lgkmcnt(0)
	v_add_f32_e32 v119, v103, v125
	v_max_i32_e32 v120, 0xfffffef1, v14
	v_max_i32_e32 v121, 0xfffffef0, v14
	v_max_i32_e32 v122, 0xfffffeef, v14
	v_max_i32_e32 v123, 0xfffffeee, v14
	v_max_i32_e32 v124, 0xfffffee9, v14
	v_max_i32_e32 v125, 0xfffffee8, v14
	v_max_i32_e32 v126, 0xfffffee7, v14
	v_max_i32_e32 v14, 0xfffffee6, v14
	v_add_f32_e32 v15, v15, v113
	v_exp_f32_e32 v117, v117
	v_lshl_add_u32 v120, v120, 2, s16
	v_lshl_add_u32 v121, v121, 2, s16
	v_lshl_add_u32 v122, v122, 2, s16
	v_lshl_add_u32 v123, v123, 2, s16
	v_lshl_add_u32 v124, v124, 2, s16
	v_lshl_add_u32 v125, v125, 2, s16
	v_lshl_add_u32 v126, v126, 2, s16
	v_lshl_add_u32 v14, v14, 2, s16
	v_add_f32_e32 v15, v15, v114
	v_exp_f32_e32 v118, v118
	ds_read_b32 v120, v120 offset:1084
	ds_read_b32 v121, v121 offset:1088
	ds_read_b32 v122, v122 offset:1092
	ds_read_b32 v123, v123 offset:1096
	ds_read_b32 v124, v124 offset:1116
	ds_read_b32 v125, v125 offset:1120
	ds_read_b32 v126, v126 offset:1124
	ds_read_b32 v14, v14 offset:1128
	v_add_f32_e32 v15, v15, v115
	v_exp_f32_e32 v119, v119
	s_waitcnt lgkmcnt(7)
	v_add_f32_e32 v120, v104, v120
	v_add_f32_e32 v15, v15, v116
	v_exp_f32_e32 v120, v120
	s_waitcnt lgkmcnt(6)
	v_add_f32_e32 v121, v105, v121
	v_add_f32_e32 v15, v15, v117
	v_exp_f32_e32 v121, v121
	s_waitcnt lgkmcnt(5)
	v_add_f32_e32 v122, v106, v122
	v_add_f32_e32 v15, v15, v118
	v_exp_f32_e32 v122, v122
	s_waitcnt lgkmcnt(4)
	v_add_f32_e32 v123, v107, v123
	v_add_f32_e32 v15, v15, v119
	v_exp_f32_e32 v123, v123
	s_waitcnt lgkmcnt(3)
	v_add_f32_e32 v124, v108, v124
	v_add_f32_e32 v15, v15, v120
	v_exp_f32_e32 v124, v124
	s_waitcnt lgkmcnt(2)
	v_add_f32_e32 v125, v109, v125
	v_add_f32_e32 v15, v15, v121
	v_exp_f32_e32 v125, v125
	s_waitcnt lgkmcnt(1)
	v_add_f32_e32 v126, v110, v126
	v_add_f32_e32 v15, v15, v122
	v_exp_f32_e32 v126, v126
	s_waitcnt lgkmcnt(0)
	v_add_f32_e32 v14, v111, v14
	v_add_f32_e32 v15, v15, v123
	v_exp_f32_e32 v127, v14
	v_add_f32_e32 v14, v15, v124
	v_add_f32_e32 v14, v14, v125
	v_add_f32_e32 v14, v14, v126
	v_add_f32_e32 v14, v14, v127
	s_mov_b64 s[22:23], 0

.LBB0_702:
	s_cmp_le_i32 s23, s39
	s_cselect_b64 s[0:1], -1, 0
	s_and_b64 s[0:1], s[30:31], s[0:1]
	s_andn2_b64 vcc, exec, s[0:1]
	s_cbranch_vccnz .LBB0_712
	s_add_i32 s0, s22, 64
	s_cmpk_gt_u32 s0, 0x420
	s_cselect_b64 s[0:1], -1, 0
	s_setprio 1
	s_mul_i32 s2, s46, 0x2400
	v_add_u32_e32 v1, s2, v215
	ds_read_b128 v[2:5], v1
	ds_read_b128 v[6:9], v1 offset:4608
	ds_read_b128 v[10:13], v1 offset:32
	ds_read_b128 v[168:171], v1 offset:4640
	s_cmp_ge_i32 s23, s40
	s_cselect_b64 s[18:19], -1, 0
	s_or_b64 s[0:1], s[18:19], s[0:1]
	v_cndmask_b32_e64 v80, v218, 0, s[0:1]
	v_mov_b32_e32 v81, v80
	v_mov_b32_e32 v82, v80
	v_mov_b32_e32 v83, v80
	v_mov_b32_e32 v84, v80
	v_mov_b32_e32 v85, v80
	v_mov_b32_e32 v86, v80
	v_mov_b32_e32 v87, v80
	v_mov_b32_e32 v88, v80
	v_mov_b32_e32 v89, v80
	v_mov_b32_e32 v90, v80
	v_mov_b32_e32 v91, v80
	v_mov_b32_e32 v92, v80
	v_mov_b32_e32 v93, v80
	v_mov_b32_e32 v94, v80
	v_mov_b32_e32 v95, v80
	s_mov_b64 s[18:19], -1
	s_waitcnt lgkmcnt(3)
	s_nop 0
	v_mfma_f32_32x32x16_bf16 v[96:111], v[2:5], v[132:135], v[80:95]
	ds_read_b128 v[2:5], v1 offset:64
	s_waitcnt lgkmcnt(3)
	v_mfma_f32_32x32x16_bf16 v[80:95], v[6:9], v[132:135], v[80:95]
	ds_read_b128 v[6:9], v1 offset:4672
	s_waitcnt lgkmcnt(3)
	v_mfma_f32_32x32x16_bf16 v[96:111], v[10:13], v[128:131], v[96:111]
	ds_read_b128 v[10:13], v1 offset:96
	s_waitcnt lgkmcnt(3)
	v_mfma_f32_32x32x16_bf16 v[80:95], v[168:171], v[128:131], v[80:95]
	ds_read_b128 v[168:171], v1 offset:4704
	s_waitcnt lgkmcnt(3)
	v_mfma_f32_32x32x16_bf16 v[96:111], v[2:5], v[140:143], v[96:111]
	s_waitcnt lgkmcnt(2)
	v_mfma_f32_32x32x16_bf16 v[80:95], v[6:9], v[140:143], v[80:95]
	s_waitcnt lgkmcnt(1)
	v_mfma_f32_32x32x16_bf16 v[96:111], v[10:13], v[136:139], v[96:111]
	s_waitcnt lgkmcnt(0)
	v_mfma_f32_32x32x16_bf16 v[80:95], v[168:171], v[136:139], v[80:95]
	s_setprio 0
	s_mul_i32 s2, s46, 0x4400
	v_add_u32_e32 v1, s2, v216
	v_add_u32_e32 v2, 0x6800, v1
	ds_read2_b64 v[6:9], v2 offset0:128 offset1:130
	ds_read2_b64 v[10:13], v2 offset0:132 offset1:134
	ds_read2_b64 v[168:171], v2 offset0:136 offset1:138
	ds_read2_b64 v[2:5], v2 offset0:140 offset1:142
	s_and_b64 vcc, exec, s[0:1]
	s_cbranch_vccnz .LBB0_705
	v_exp_f32_e32 v112, v96
	v_exp_f32_e32 v113, v97
	v_exp_f32_e32 v114, v98
	v_exp_f32_e32 v115, v99
	v_add_f32_e32 v14, v191, v112
	v_exp_f32_e32 v116, v100
	v_add_f32_e32 v14, v113, v14
	v_exp_f32_e32 v117, v101
	v_add_f32_e32 v14, v114, v14
	v_exp_f32_e32 v118, v102
	v_add_f32_e32 v14, v115, v14
	v_exp_f32_e32 v119, v103
	v_add_f32_e32 v14, v116, v14
	v_exp_f32_e32 v120, v104
	v_add_f32_e32 v14, v117, v14
	v_exp_f32_e32 v121, v105
	v_add_f32_e32 v14, v118, v14
	v_exp_f32_e32 v122, v106
	v_add_f32_e32 v14, v119, v14
	v_exp_f32_e32 v123, v107
	v_add_f32_e32 v14, v120, v14
	v_exp_f32_e32 v124, v108
	v_add_f32_e32 v14, v121, v14
	v_exp_f32_e32 v125, v109
	v_add_f32_e32 v14, v122, v14
	v_exp_f32_e32 v126, v110
	v_add_f32_e32 v14, v123, v14
	v_exp_f32_e32 v127, v111
	v_add_f32_e32 v14, v124, v14
	v_add_f32_e32 v14, v125, v14
	v_add_f32_e32 v14, v126, v14
	v_add_f32_e32 v193, v127, v14
	s_mov_b64 s[18:19], 0

.LBB0_717:
	s_cmp_lt_i32 s23, s39
	s_cselect_b64 s[0:1], -1, 0
	s_and_b64 s[0:1], s[30:31], s[0:1]
	s_andn2_b64 vcc, exec, s[0:1]
	s_cbranch_vccnz .LBB0_727
	s_setprio 1
	s_mul_i32 s0, s50, 0x2400
	v_add_u32_e32 v1, s0, v215
	ds_read_b128 v[2:5], v1
	ds_read_b128 v[6:9], v1 offset:4608
	ds_read_b128 v[10:13], v1 offset:32
	ds_read_b128 v[168:171], v1 offset:4640
	s_cmp_ge_i32 s47, s40
	s_cselect_b64 s[0:1], -1, 0
	s_cmp_lt_i32 s47, s40
	s_cselect_b64 vcc, -1, 0
	v_cndmask_b32_e32 v80, 0, v218, vcc
	v_mov_b32_e32 v81, v80
	v_mov_b32_e32 v82, v80
	v_mov_b32_e32 v83, v80
	v_mov_b32_e32 v84, v80
	v_mov_b32_e32 v85, v80
	v_mov_b32_e32 v86, v80
	v_mov_b32_e32 v87, v80
	v_mov_b32_e32 v88, v80
	v_mov_b32_e32 v89, v80
	v_mov_b32_e32 v90, v80
	v_mov_b32_e32 v91, v80
	v_mov_b32_e32 v92, v80
	v_mov_b32_e32 v93, v80
	v_mov_b32_e32 v94, v80
	v_mov_b32_e32 v95, v80
	s_waitcnt lgkmcnt(3)
	s_nop 0
	v_mfma_f32_32x32x16_bf16 v[96:111], v[2:5], v[132:135], v[80:95]
	ds_read_b128 v[2:5], v1 offset:64
	s_waitcnt lgkmcnt(3)
	v_mfma_f32_32x32x16_bf16 v[80:95], v[6:9], v[132:135], v[80:95]
	ds_read_b128 v[6:9], v1 offset:4672
	s_waitcnt lgkmcnt(3)
	v_mfma_f32_32x32x16_bf16 v[96:111], v[10:13], v[128:131], v[96:111]
	ds_read_b128 v[10:13], v1 offset:96
	s_waitcnt lgkmcnt(3)
	v_mfma_f32_32x32x16_bf16 v[80:95], v[168:171], v[128:131], v[80:95]
	ds_read_b128 v[168:171], v1 offset:4704
	s_waitcnt lgkmcnt(3)
	v_mfma_f32_32x32x16_bf16 v[96:111], v[2:5], v[140:143], v[96:111]
	s_waitcnt lgkmcnt(2)
	v_mfma_f32_32x32x16_bf16 v[80:95], v[6:9], v[140:143], v[80:95]
	s_waitcnt lgkmcnt(1)
	v_mfma_f32_32x32x16_bf16 v[96:111], v[10:13], v[136:139], v[96:111]
	s_waitcnt lgkmcnt(0)
	v_mfma_f32_32x32x16_bf16 v[80:95], v[168:171], v[136:139], v[80:95]
	s_setprio 0
	s_mul_i32 s2, s50, 0x4400
	v_add_u32_e32 v1, s2, v216
	v_add_u32_e32 v2, 0x6800, v1
	ds_read2_b64 v[6:9], v2 offset0:128 offset1:130
	ds_read2_b64 v[10:13], v2 offset0:132 offset1:134
	ds_read2_b64 v[168:171], v2 offset0:136 offset1:138
	ds_read2_b64 v[2:5], v2 offset0:140 offset1:142
	v_add_u32_e32 v193, s22, v184
	v_add_u32_e32 v195, s22, v217
	v_add_u32_e32 v14, 64, v193
	s_mov_b64 s[18:19], -1
	s_and_b64 vcc, exec, s[0:1]
	v_add_u32_e32 v15, 0xfffffc40, v195
	s_cbranch_vccz .LBB0_720
	v_max_i32_e32 v112, 0xffffff01, v15
	v_max_i32_e32 v113, 0xffffff00, v15
	v_max_i32_e32 v114, 0xfffffeff, v15
	v_max_i32_e32 v115, 0xfffffefe, v15
	v_max_i32_e32 v116, 0xfffffef9, v15
	v_max_i32_e32 v117, 0xfffffef8, v15
	v_max_i32_e32 v118, 0xfffffef7, v15
	v_max_i32_e32 v119, 0xfffffef6, v15
	v_lshl_add_u32 v112, v112, 2, s16
	v_lshl_add_u32 v113, v113, 2, s16
	v_lshl_add_u32 v114, v114, 2, s16
	v_lshl_add_u32 v115, v115, 2, s16
	v_lshl_add_u32 v116, v116, 2, s16
	v_lshl_add_u32 v117, v117, 2, s16
	v_lshl_add_u32 v118, v118, 2, s16
	v_lshl_add_u32 v119, v119, 2, s16
	ds_read_b32 v112, v112 offset:1020
	ds_read_b32 v113, v113 offset:1024
	ds_read_b32 v114, v114 offset:1028
	ds_read_b32 v115, v115 offset:1032
	ds_read_b32 v116, v116 offset:1052
	ds_read_b32 v117, v117 offset:1056
	ds_read_b32 v118, v118 offset:1060
	ds_read_b32 v119, v119 offset:1064
	s_waitcnt lgkmcnt(7)
	v_add_f32_e32 v112, v96, v112
	v_exp_f32_e32 v112, v112
	s_waitcnt lgkmcnt(6)
	v_add_f32_e32 v113, v97, v113
	v_exp_f32_e32 v113, v113
	s_waitcnt lgkmcnt(5)
	v_add_f32_e32 v114, v98, v114
	v_exp_f32_e32 v114, v114
	s_waitcnt lgkmcnt(4)
	v_add_f32_e32 v115, v99, v115
	v_exp_f32_e32 v115, v115
	s_waitcnt lgkmcnt(3)
	v_add_f32_e32 v116, v100, v116
	v_add_f32_e32 v120, v191, v112
	v_exp_f32_e32 v116, v116
	s_waitcnt lgkmcnt(2)
	v_add_f32_e32 v117, v101, v117
	v_add_f32_e32 v120, v120, v113
	v_exp_f32_e32 v117, v117
	s_waitcnt lgkmcnt(1)
	v_add_f32_e32 v118, v102, v118
	v_add_f32_e32 v120, v120, v114
	v_exp_f32_e32 v118, v118
	v_add_f32_e32 v120, v120, v115
	v_add_f32_e32 v120, v120, v116
	v_add_f32_e32 v120, v120, v117
	v_add_f32_e32 v123, v120, v118
	v_max_i32_e32 v120, 0xfffffef1, v15
	v_max_i32_e32 v121, 0xfffffef0, v15
	v_max_i32_e32 v122, 0xfffffeef, v15
	v_max_i32_e32 v124, 0xfffffeee, v15
	v_max_i32_e32 v125, 0xfffffee9, v15
	v_max_i32_e32 v126, 0xfffffee8, v15
	v_max_i32_e32 v127, 0xfffffee7, v15
	v_max_i32_e32 v219, 0xfffffee6, v15
	v_lshl_add_u32 v120, v120, 2, s16
	v_lshl_add_u32 v121, v121, 2, s16
	v_lshl_add_u32 v122, v122, 2, s16
	v_lshl_add_u32 v124, v124, 2, s16
	v_lshl_add_u32 v125, v125, 2, s16
	v_lshl_add_u32 v126, v126, 2, s16
	v_lshl_add_u32 v127, v127, 2, s16
	v_lshl_add_u32 v219, v219, 2, s16
	s_waitcnt lgkmcnt(0)
	v_add_f32_e32 v119, v103, v119
	ds_read_b32 v120, v120 offset:1084
	ds_read_b32 v121, v121 offset:1088
	ds_read_b32 v122, v122 offset:1092
	ds_read_b32 v124, v124 offset:1096
	ds_read_b32 v125, v125 offset:1116
	ds_read_b32 v126, v126 offset:1120
	ds_read_b32 v127, v127 offset:1124
	ds_read_b32 v219, v219 offset:1128
	v_exp_f32_e32 v119, v119
	s_waitcnt lgkmcnt(7)
	v_add_f32_e32 v120, v104, v120
	v_exp_f32_e32 v120, v120
	s_waitcnt lgkmcnt(6)
	v_add_f32_e32 v121, v105, v121
	v_exp_f32_e32 v121, v121
	s_waitcnt lgkmcnt(5)
	v_add_f32_e32 v122, v106, v122
	v_exp_f32_e32 v122, v122
	v_add_f32_e32 v123, v123, v119
	v_add_f32_e32 v123, v120, v123
	v_add_f32_e32 v123, v123, v121
	v_add_f32_e32 v227, v123, v122
	s_waitcnt lgkmcnt(4)
	v_add_f32_e32 v123, v107, v124
	v_exp_f32_e32 v123, v123
	s_waitcnt lgkmcnt(3)
	v_add_f32_e32 v124, v108, v125
	s_waitcnt lgkmcnt(2)
	v_add_f32_e32 v125, v109, v126
	v_exp_f32_e32 v124, v124
	v_exp_f32_e32 v125, v125
	s_movk_i32 s2, 0x407
	v_add_f32_e32 v126, v227, v123
	v_cmp_gt_u32_e32 vcc, s2, v14
	v_add_f32_e32 v126, v124, v126
	s_movk_i32 s2, 0x406
	v_cndmask_b32_e32 v125, 0, v125, vcc
	v_add_f32_e32 v227, v126, v125
	s_waitcnt lgkmcnt(1)
	v_add_f32_e32 v126, v110, v127
	v_exp_f32_e32 v126, v126
	s_waitcnt lgkmcnt(0)
	v_add_f32_e32 v127, v111, v219
	v_exp_f32_e32 v127, v127
	v_cmp_gt_u32_e32 vcc, s2, v14
	s_movk_i32 s2, 0x405
	s_mov_b64 s[18:19], 0
	v_cndmask_b32_e32 v126, 0, v126, vcc
	v_cmp_gt_u32_e32 vcc, s2, v14
	v_add_f32_e32 v219, v227, v126
	s_nop 0
	v_cndmask_b32_e32 v127, 0, v127, vcc
	v_add_f32_e32 v219, v219, v127
